# scan loop runs at s_setprio 1 instead of 2 (priority 3 was 13 us slower: the staging waves starve)
# baseline (speedup 1.0000x reference)
; #define LAS __attribute__((address_space(3)))
;     __device__ __forceinline__ const float* in(int i) const { return (const float*)ptr(i); }
;     __device__ __forceinline__ float* out() const { return (float*)ptr(36); }
;     __device__ __forceinline__ unsigned char* ws() const { return (unsigned char*)ptr(37); }
; #define ws (p.ws())
; __device__ __forceinline__ void scan_unit(const Ctx& p, int chain, int rq, LAS unsigned char* lds) {
;     ...
;     const int cb = smp ? (chain - 32) >> 3 : chain >> 3, h = chain & 7, T = smp ? TS : TP, row0 = smp ? MPR + cb * TS : cb * TP;
;     const int nch = T / SCH;
;     const bf16_t* ZRW = (const bf16_t*)(p.ws() + WS_ZRW);
;     const float* DEC = (const float*)(p.ws() + WS_DEC); const bf16_t* AB = (const bf16_t*)(p.ws() + WS_ABUF);
;     bf16_t* ORW = (bf16_t*)(p.ws() + WS_ORW);
;     LAS float* B0 = (LAS float*)lds; LAS float* YB = B0 + 2 * SBUF_F;
;     __syncthreads();
;     if (wave >= 4) {
;     ...
;         const int rl = lane >> 4, cl = lane & 15, il = 4 * wave + rl;
;         f32x4 S;
;         float* sg = (smp ? p.out() + O_SS : p.out() + O_SP) + ((size_t)(cb * 8 + h) * 64 + 16 * rq + il) * 64 + 4 * cl;
;         if (smp) S = *(const f32x4*)(p.in(4) + ((size_t)(cb * 8 + h) * 64 + 16 * rq + il) * 64 + 4 * cl); else S = (f32x4){0.f, 0.f, 0.f, 0.f};
;         for (int ci = 0; ci < nch; ++ci) {
;             __syncthreads();
;             const LAS float* OP = B0 + (ci & 1) * SBUF_F + 4 * cl;
;             const LAS float* VP = B0 + (ci & 1) * SBUF_F + SCH * 320 + il * 16;
;             LAS float* Y = YB + (ci & 1) * YP_F + il * 16 + cl;
;             ScanOps oa, ob;
;             scan_load(oa, OP, VP, 0);
;             f32x2 vv = *(const LAS f32x2*)VP;
; #pragma unroll 1
;             for (int t = 0; t < SCH; t += 2) {
.LBB0_1711:
	s_and_b64 vcc, exec, s[2:3]
	s_cbranch_vccz .LBB0_1750
	s_add_i32 s2, 0, 0x23528
	s_waitcnt vmcnt(0)
	v_mov_b32_e32 v0, s2
	ds_read_b64 v[0:1], v0
	v_readfirstlane_b32 s8, v180
	s_mov_b32 s10, 0
	s_cmpk_lt_u32 s8, 0x100
	s_mov_b64 s[2:3], -1
	s_waitcnt lgkmcnt(0)
	v_readfirstlane_b32 s4, v0
	v_readfirstlane_b32 s5, v1
	s_barrier
	s_cbranch_scc0 .LBB0_1718
	s_add_i32 s2, 0, 0x23520
	v_mov_b32_e32 v0, s2
	ds_read_b64 v[0:1], v0
	v_bfe_u32 v2, v180, 4, 2
	v_and_b32_e32 v3, 15, v180
	s_lshr_b32 s2, s8, 4
	s_lshl_b32 s8, s8, 2
	v_and_or_b32 v27, s2, 12, v2
	s_waitcnt lgkmcnt(0)
	v_readfirstlane_b32 s2, v0
	v_lshlrev_b32_e32 v26, 2, v3
	s_and_b32 s8, s8, 0x300
	v_lshlrev_b32_e32 v0, 6, v2
	v_or3_b32 v0, s8, v0, v26
	v_add_u32_e32 v0, 0, v0
	v_add_u32_e32 v29, 0xa800, v0
	v_lshl_add_u32 v0, v3, 4, 0
	v_add_u32_e32 v30, 0x500, v0
	v_mov_b32_e32 v0, 0
	v_readfirstlane_b32 s3, v1
	v_lshlrev_b32_e32 v28, 4, v27
	s_mov_b64 s[8:9], 0
	s_movk_i32 s11, 0x5400
	v_mov_b32_e32 v1, v0
	v_mov_b32_e32 v2, v0
	v_mov_b32_e32 v3, v0
	s_setprio 1
	.p2align 3
